# small-gemm K-section coalesced (P1,P3,P6b): full-line loads + LDS transpose
# speedup vs baseline: 1.0187x; 1.0088x over previous
; #define HG_MFMA(a, b, c) __builtin_amdgcn_mfma_f32_32x32x16_bf16((a), (b), (c), 0, 0, 0)
;     __device__ __forceinline__ void small_pre(int row, int c0, int c1, SPre& sp) const { sp.ss = sumsq2[row]; sp.h0 = unpack4(*(const u32x2*)(HB + (size_t)row * DM + c0)); sp.h1 = unpack4(*(const u32x2*)(HB + (size_t)row * DM + c1)); }
; template <int K, class Epi>
; __device__ __forceinline__ void small_gemm(unsigned char* lds, const bf16_t* A, const bf16_t* Bt, int row0, int br0, int br1, const Epi& E) {
;     int tid = threadIdx.x; asm volatile("" : "+v"(tid));
;     const int w = __builtin_amdgcn_readfirstlane(tid >> 6), lane = tid & 63, r = lane & 31, hh = lane >> 5;
;     constexpr int ks = K >> 3, NS = ks >> 4, UNR = NS <= 8 ? NS : 11; const int k0 = w * ks + 8 * hh;
;     const bf16_t* ap = A + (size_t)(row0 + r) * K + k0; const bf16_t* b0p = Bt + (size_t)(br0 + r) * K + k0; const bf16_t* b1p = Bt + (size_t)(br1 + r) * K + k0;
;     typename Epi::SPre spre; const int srow = row0 + ((tid >> 3) & 31), sc4 = (tid & 7) * 4;
;     if (tid < 256) E.small_pre(srow, br0 + sc4, br1 + sc4, spre);
;     f32x16 acc0, acc1;
; #pragma unroll
;     for (int i = 0; i < 16; ++i) { acc0[i] = 0.f; acc1[i] = 0.f; }
; #pragma unroll UNR
;     for (int s = 0; s < NS; ++s) { const bf16x8 a = *(const bf16x8*)(ap + 16 * s), b0 = *(const bf16x8*)(b0p + 16 * s), b1 = *(const bf16x8*)(b1p + 16 * s);
;         acc0 = HG_MFMA(a, b0, acc0); acc1 = HG_MFMA(a, b1, acc1); }
;     float* part = (float*)lds + (size_t)w * (2 * 32 * SG_P);
.LBB0_245:
	s_or_b64 exec, exec, s[12:13]
	s_lshl_b32 s14, s16, 5
	s_add_i32 s4, s14, 0x4000
	v_and_b32_e32 v76, 31, v44
	v_bfe_u32 v77, v44, 5, 1
	s_ashr_i32 s5, s25, 6
	s_waitcnt lgkmcnt(0)
	s_lshl_b32 s37, s5, 8
	s_lshl_b32 s36, s4, 11
	s_add_i32 s36, s36, s37
	s_add_u32 s38, s82, s36
	s_addc_u32 s39, s83, 0
	s_lshl_b32 s36, s17, 11
	s_add_i32 s36, s36, s37
	s_add_u32 s40, s64, s36
	s_addc_u32 s41, s65, 0
	s_lshl_b32 s36, s24, 11
	s_add_i32 s36, s36, s37
	s_add_u32 s42, s64, s36
	s_addc_u32 s43, s65, 0
	v_and_b32_e32 v60, 63, v44
	v_lshrrev_b32_e32 v61, 4, v60
	v_and_b32_e32 v62, 7, v60
	v_xor_b32_e32 v62, v62, v61
	v_lshrrev_b32_e32 v61, 3, v60
	v_lshlrev_b32_e32 v62, 4, v62
	v_lshl_or_b32 v64, v61, 11, v62
	v_xor_b32_e32 v65, 64, v64
	v_add_u32_e32 v65, 0x4000, v65
	v_add_u32_e32 v66, 0x8000, v64
	v_xor_b32_e32 v67, 64, v64
	v_add_u32_e32 v67, 0xc000, v67
	global_load_dwordx4 v[88:91], v64, s[38:39]
	global_load_dwordx4 v[92:95], v65, s[38:39]
	global_load_dwordx4 v[96:99], v66, s[38:39]
	global_load_dwordx4 v[100:103], v67, s[38:39]
	global_load_dwordx4 v[104:107], v64, s[40:41]
	global_load_dwordx4 v[108:111], v65, s[40:41]
	global_load_dwordx4 v[112:115], v66, s[40:41]
	global_load_dwordx4 v[116:119], v67, s[40:41]
	global_load_dwordx4 v[120:123], v64, s[42:43]
	global_load_dwordx4 v[124:127], v65, s[42:43]
	global_load_dwordx4 v[128:131], v66, s[42:43]
	global_load_dwordx4 v[132:135], v67, s[42:43]
	global_load_dwordx4 v[136:139], v64, s[38:39] offset:128
	global_load_dwordx4 v[140:143], v65, s[38:39] offset:128
	global_load_dwordx4 v[144:147], v66, s[38:39] offset:128
	global_load_dwordx4 v[148:151], v67, s[38:39] offset:128
	global_load_dwordx4 v[152:155], v64, s[40:41] offset:128
	global_load_dwordx4 v[156:159], v65, s[40:41] offset:128
	global_load_dwordx4 v[160:163], v66, s[40:41] offset:128
	global_load_dwordx4 v[164:167], v67, s[40:41] offset:128
	global_load_dwordx4 v[168:171], v64, s[42:43] offset:128
	global_load_dwordx4 v[172:175], v65, s[42:43] offset:128
	global_load_dwordx4 v[180:183], v66, s[42:43] offset:128
	global_load_dwordx4 v[184:187], v67, s[42:43] offset:128
	s_mul_i32 s46, s5, 0x3000
	v_lshl_add_u32 v68, v60, 4, s46
	v_lshl_add_u32 v69, v76, 7, s46
	v_bfe_u32 v63, v76, 1, 3
	v_or_b32_e32 v46, 0, v77
	v_xor_b32_e32 v46, v46, v63
	v_lshl_add_u32 v46, v46, 4, v69
	v_or_b32_e32 v47, 2, v77
	v_xor_b32_e32 v47, v47, v63
	v_lshl_add_u32 v47, v47, 4, v69
	v_or_b32_e32 v48, 4, v77
	v_xor_b32_e32 v48, v48, v63
	v_lshl_add_u32 v48, v48, 4, v69
	v_or_b32_e32 v49, 6, v77
	v_xor_b32_e32 v49, v49, v63
	v_lshl_add_u32 v49, v49, 4, v69
	s_mulk_i32 s5, 0x2400
	v_lshlrev_b32_e32 v40, 2, v76
	s_add_i32 s5, s5, 0
	v_mul_u32_u24_e32 v58, 0x90, v77
	v_lshlrev_b32_e32 v54, 2, v58
	v_add3_u32 v55, s5, v40, v54
	v_add3_u32 v40, s5, v54, v40
	v_add_u32_e32 v54, 0x1000, v40
	v_add_u32_e32 v56, 0x400, v55
	v_add_u32_e32 v57, 0x1400, v40
	v_add_u32_e32 v58, 0xc00, v55
	v_add_u32_e32 v59, 0x1e00, v40
	s_waitcnt vmcnt(12)
	ds_write_b128 v68, v[88:91]
	ds_write_b128 v68, v[92:95] offset:1024
	ds_write_b128 v68, v[96:99] offset:2048
	ds_write_b128 v68, v[100:103] offset:3072
	ds_write_b128 v68, v[104:107] offset:4096
	ds_write_b128 v68, v[108:111] offset:5120
	ds_write_b128 v68, v[112:115] offset:6144
	ds_write_b128 v68, v[116:119] offset:7168
	ds_write_b128 v68, v[120:123] offset:8192
	ds_write_b128 v68, v[124:127] offset:9216
	ds_write_b128 v68, v[128:131] offset:10240
	ds_write_b128 v68, v[132:135] offset:11264
	s_waitcnt lgkmcnt(0)
	ds_read_b128 v[192:195], v46
	ds_read_b128 v[212:215], v46 offset:4096
	ds_read_b128 v[228:231], v46 offset:8192
	ds_read_b128 v[196:199], v47
	ds_read_b128 v[216:219], v47 offset:4096
	ds_read_b128 v[232:235], v47 offset:8192
	ds_read_b128 v[200:203], v48
	ds_read_b128 v[220:223], v48 offset:4096
	ds_read_b128 v[236:239], v48 offset:8192
	ds_read_b128 v[208:211], v49
	ds_read_b128 v[224:227], v49 offset:4096
	ds_read_b128 v[240:243], v49 offset:8192
	s_waitcnt lgkmcnt(9)
	v_mfma_f32_32x32x16_bf16 v[0:15], v[192:195], v[212:215], 0
	v_mfma_f32_32x32x16_bf16 v[16:31], v[192:195], v[228:231], 0
	s_waitcnt lgkmcnt(6)
	v_mfma_f32_32x32x16_bf16 v[0:15], v[196:199], v[216:219], v[0:15]
	v_mfma_f32_32x32x16_bf16 v[16:31], v[196:199], v[232:235], v[16:31]
	s_waitcnt lgkmcnt(3)
	v_mfma_f32_32x32x16_bf16 v[0:15], v[200:203], v[220:223], v[0:15]
	v_mfma_f32_32x32x16_bf16 v[16:31], v[200:203], v[236:239], v[16:31]
	s_waitcnt lgkmcnt(0)
	v_mfma_f32_32x32x16_bf16 v[0:15], v[208:211], v[224:227], v[0:15]
	v_mfma_f32_32x32x16_bf16 v[16:31], v[208:211], v[240:243], v[16:31]
	s_waitcnt vmcnt(0)
	ds_write_b128 v68, v[136:139]
	ds_write_b128 v68, v[140:143] offset:1024
	ds_write_b128 v68, v[144:147] offset:2048
	ds_write_b128 v68, v[148:151] offset:3072
	ds_write_b128 v68, v[152:155] offset:4096
	ds_write_b128 v68, v[156:159] offset:5120
	ds_write_b128 v68, v[160:163] offset:6144
	ds_write_b128 v68, v[164:167] offset:7168
	ds_write_b128 v68, v[168:171] offset:8192
	ds_write_b128 v68, v[172:175] offset:9216
	ds_write_b128 v68, v[180:183] offset:10240
	ds_write_b128 v68, v[184:187] offset:11264
	s_waitcnt lgkmcnt(0)
	ds_read_b128 v[192:195], v46
	ds_read_b128 v[212:215], v46 offset:4096
	ds_read_b128 v[228:231], v46 offset:8192
	ds_read_b128 v[196:199], v47
	ds_read_b128 v[216:219], v47 offset:4096
	ds_read_b128 v[232:235], v47 offset:8192
	ds_read_b128 v[200:203], v48
	ds_read_b128 v[220:223], v48 offset:4096
	ds_read_b128 v[236:239], v48 offset:8192
	ds_read_b128 v[208:211], v49
	ds_read_b128 v[224:227], v49 offset:4096
	ds_read_b128 v[240:243], v49 offset:8192
	s_waitcnt lgkmcnt(9)
	v_mfma_f32_32x32x16_bf16 v[0:15], v[192:195], v[212:215], v[0:15]
	v_mfma_f32_32x32x16_bf16 v[16:31], v[192:195], v[228:231], v[16:31]
	s_waitcnt lgkmcnt(6)
	v_mfma_f32_32x32x16_bf16 v[0:15], v[196:199], v[216:219], v[0:15]
	v_mfma_f32_32x32x16_bf16 v[16:31], v[196:199], v[232:235], v[16:31]
	s_waitcnt lgkmcnt(3)
	v_mfma_f32_32x32x16_bf16 v[0:15], v[200:203], v[220:223], v[0:15]
	v_mfma_f32_32x32x16_bf16 v[16:31], v[200:203], v[236:239], v[16:31]
	s_waitcnt lgkmcnt(0)
	v_mfma_f32_32x32x16_bf16 v[0:15], v[208:211], v[224:227], v[0:15]
	v_add_u32_e32 v50, 0x1600, v40
	v_add_u32_e32 v51, 0x800, v55
	v_add_u32_e32 v52, 0x1800, v40
	v_add_u32_e32 v53, 0x1c00, v40
	v_add_u32_e32 v40, 0x2000, v40
	v_mfma_f32_32x32x16_bf16 v[16:31], v[208:211], v[240:243], v[16:31]
	s_barrier
; __device__ __forceinline__ unsigned cvt_pk_bf16(float lo, float hi) { unsigned r; asm volatile("v_cvt_pk_bf16_f32 %0, %1, %2" : "=v"(r) : "v"(lo), "v"(hi)); return r; }
; __device__ __forceinline__ float sigmoidf_(float x) { return frcp(1.0f + __expf(-x)); }
; #define LDS_BARRIER() do { asm volatile("s_waitcnt lgkmcnt(0)" ::: "memory"); __builtin_amdgcn_s_barrier(); asm volatile("" ::: "memory"); } while (0)
; template <int K, class Epi>
; __device__ __forceinline__ void small_gemm(unsigned char* lds, const bf16_t* A, const bf16_t* Bt, int row0, int br0, int br1, const Epi& E) {
;     ...
;     float* part = (float*)lds + (size_t)w * (2 * 32 * SG_P);
; #pragma unroll
;     for (int g = 0; g < 4; ++g)
; #pragma unroll
;         for (int i = 0; i < 4; ++i) { part[(8 * g + 4 * hh + i) * SG_P + r] = acc0[4 * g + i]; part[(32 + 8 * g + 4 * hh + i) * SG_P + r] = acc1[4 * g + i]; }
;     LDS_BARRIER();
;     if (tid < 256) { const int row = tid >> 3, c4 = (tid & 7) * 4; f32x4 v0 = {0.f, 0.f, 0.f, 0.f}, v1 = {0.f, 0.f, 0.f, 0.f};
; #pragma unroll
;         for (int ww = 0; ww < 8; ++ww) { const float* pp = (const float*)lds + (size_t)ww * (2 * 32 * SG_P); v0 += *(const f32x4*)(pp + row * SG_P + c4); v1 += *(const f32x4*)(pp + (32 + row) * SG_P + c4); }
;         E.small(row0 + row, br0 + c4, br1 + c4, v0, v1, spre); }
;     __device__ __forceinline__ void small(int row, int c0p, int c1p, const f32x4& v0, const f32x4& v1, const SPre& sp) const {
;     ...
;         } else { const int n1 = c0 - 2048, cu = (n1 >> 8) * 128 + (n1 & 127); f32x4 uu;
; #pragma unroll
;             for (int j = 0; j < 4; ++j) uu[j] = v0[j] * sigmoidf_(v1[j]);
;             u32x2 w; w.x = cvt_pk_bf16(uu[0], uu[1]); w.y = cvt_pk_bf16(uu[2], uu[3]); *(u32x2*)(U + (size_t)row * 512 + cu) = w;
;             const int rs = row - MP; __builtin_nontemporal_store(uu, (f32x4*)(scs + ((size_t)((rs >> 2) * (CW - 1) + (CW - 1 - DS) + (rs & 3))) * MIXB + cu)); }
	s_nop 5
	ds_write2_b32 v55, v0, v1 offset1:36
	s_nop 4
	ds_write2_b32 v54, v16, v17 offset0:128 offset1:164
	ds_write2_b32 v55, v2, v3 offset0:72 offset1:108
	ds_write2_b32 v54, v18, v19 offset0:200 offset1:236
	ds_write2_b32 v56, v4, v5 offset0:32 offset1:68
	ds_write2_b32 v57, v20, v21 offset0:160 offset1:196
	ds_write2_b32 v56, v6, v7 offset0:104 offset1:140
	ds_write2_b32 v50, v22, v23 offset0:104 offset1:140
	ds_write2_b32 v51, v8, v9 offset0:64 offset1:100
	ds_write2_b32 v52, v24, v25 offset0:192 offset1:228
	ds_write2_b32 v51, v10, v11 offset0:136 offset1:172
	ds_write2_b32 v53, v26, v27 offset0:8 offset1:44
	ds_write2_b32 v58, v12, v13 offset0:96 offset1:132
	ds_write2_b32 v59, v28, v29 offset0:96 offset1:132
	ds_write2_b32 v58, v14, v15 offset0:168 offset1:204
	ds_write2_b32 v40, v30, v31 offset0:40 offset1:76
	s_waitcnt lgkmcnt(0)
	s_barrier
	s_and_saveexec_b64 s[12:13], vcc
	s_cbranch_execz .LBB0_236
	v_ashrrev_i32_e32 v10, 3, v44
	v_mul_lo_u32 v0, v10, s20
	v_lshlrev_b32_e32 v1, 2, v42
	v_add3_u32 v11, 0, v0, v1
	ds_read_b128 v[0:3], v11
	ds_read_b128 v[4:7], v11 offset:4608
	ds_read_b128 v[12:15], v11 offset:9216
	ds_read_b128 v[16:19], v11 offset:64512
	s_waitcnt lgkmcnt(0)
	v_pk_add_f32 v[8:9], v[2:3], 0 op_sel_hi:[1,0]
	v_pk_add_f32 v[20:21], v[0:1], 0 op_sel_hi:[1,0]
	ds_read_b128 v[0:3], v11 offset:13824
	v_pk_add_f32 v[22:23], v[6:7], 0 op_sel_hi:[1,0]
	v_pk_add_f32 v[24:25], v[4:5], 0 op_sel_hi:[1,0]
	ds_read_b128 v[4:7], v11 offset:18432
	v_pk_add_f32 v[8:9], v[8:9], v[14:15]
	v_pk_add_f32 v[20:21], v[20:21], v[12:13]
	s_waitcnt lgkmcnt(1)
	v_pk_add_f32 v[22:23], v[22:23], v[2:3]
	ds_read_b128 v[12:15], v11 offset:23040
	v_pk_add_f32 v[24:25], v[24:25], v[0:1]
	ds_read_b128 v[0:3], v11 offset:27648
	s_waitcnt lgkmcnt(2)
	v_pk_add_f32 v[6:7], v[8:9], v[6:7]
	v_pk_add_f32 v[8:9], v[20:21], v[4:5]
	s_waitcnt lgkmcnt(1)
	v_pk_add_f32 v[20:21], v[22:23], v[14:15]
	v_pk_add_f32 v[24:25], v[24:25], v[12:13]
	s_waitcnt lgkmcnt(0)
	v_pk_add_f32 v[26:27], v[6:7], v[2:3]
	ds_read_b128 v[2:5], v11 offset:32256
	v_pk_add_f32 v[28:29], v[8:9], v[0:1]
	ds_read_b128 v[6:9], v11 offset:36864
	v_add_u32_e32 v0, 0xfc00, v11
	ds_read_b128 v[12:15], v0 offset:4608
	s_waitcnt lgkmcnt(2)
	v_pk_add_f32 v[4:5], v[20:21], v[4:5]
	ds_read_b128 v[20:23], v11 offset:41472
	v_pk_add_f32 v[24:25], v[24:25], v[2:3]
	ds_read_b128 v[0:3], v11 offset:46080
	s_waitcnt lgkmcnt(3)
	v_pk_add_f32 v[8:9], v[26:27], v[8:9]
	v_pk_add_f32 v[26:27], v[28:29], v[6:7]
	s_waitcnt lgkmcnt(1)
	v_pk_add_f32 v[28:29], v[4:5], v[22:23]
	ds_read_b128 v[4:7], v11 offset:50688
	s_waitcnt lgkmcnt(1)
	v_pk_add_f32 v[8:9], v[8:9], v[2:3]
	v_pk_add_f32 v[26:27], v[26:27], v[0:1]
	ds_read_b128 v[0:3], v11 offset:59904
	v_pk_add_f32 v[24:25], v[24:25], v[20:21]
	ds_read_b128 v[20:23], v11 offset:55296
	s_waitcnt lgkmcnt(2)
	v_pk_add_f32 v[6:7], v[28:29], v[6:7]
	v_pk_add_f32 v[4:5], v[24:25], v[4:5]
	s_waitcnt lgkmcnt(1)
	v_pk_add_f32 v[2:3], v[6:7], v[2:3]
	v_pk_add_f32 v[4:5], v[4:5], v[0:1]
	v_pk_add_f32 v[0:1], v[2:3], v[14:15]
	v_pk_add_f32 v[2:3], v[4:5], v[12:13]
	v_and_b32_e32 v5, 0x7c, v45
	v_lshrrev_b64 v[12:13], v5, s[6:7]
	v_lshlrev_b32_e32 v11, 8, v12
	s_waitcnt lgkmcnt(0)
	v_pk_add_f32 v[8:9], v[8:9], v[22:23]
	v_pk_add_f32 v[20:21], v[26:27], v[20:21]
	v_add_u32_e32 v4, s4, v10
	v_and_b32_e32 v12, 0xf00, v11
	v_pk_add_f32 v[6:7], v[8:9], v[18:19]
	v_pk_add_f32 v[8:9], v[20:21], v[16:17]
	v_cmp_lt_u32_e32 vcc, s21, v12
	v_ashrrev_i32_e32 v5, 31, v4
	s_and_saveexec_b64 s[4:5], vcc
	s_xor_b64 s[4:5], exec, s[4:5]
	s_cbranch_execz .LBB0_248
	v_mul_f32_e32 v0, 0xbfb8aa3b, v0
	v_mul_f32_e32 v2, 0xbfb8aa3b, v2
	v_mul_f32_e32 v3, 0xbfb8aa3b, v3
	v_exp_f32_e32 v0, v0
	v_mul_f32_e32 v1, 0xbfb8aa3b, v1
	v_exp_f32_e32 v2, v2
	v_exp_f32_e32 v3, v3
	v_exp_f32_e32 v1, v1
	v_add_f32_e32 v0, 1.0, v0
	v_add_f32_e32 v2, 1.0, v2
	v_add_f32_e32 v3, 1.0, v3
	v_rcp_f32_e32 v14, v0
	v_add_f32_e32 v0, 1.0, v1
	v_rcp_f32_e32 v2, v2
	v_rcp_f32_e32 v3, v3
	v_rcp_f32_e32 v15, v0
	v_add_u32_e32 v11, 0xfffff800, v12
	v_readlane_b32 s16, v247, 36
	v_pk_mul_f32 v[0:1], v[8:9], v[2:3]
	v_pk_mul_f32 v[2:3], v[6:7], v[14:15]
	v_lshrrev_b32_e32 v6, 1, v11
	v_and_or_b32 v40, v43, s22, v6
	v_lshlrev_b64 v[4:5], 10, v[4:5]
	v_readlane_b32 s17, v247, 37
	v_lshlrev_b32_e32 v8, 1, v40
	v_mov_b32_e32 v9, v41
	v_lshl_add_u64 v[4:5], s[16:17], 0, v[4:5]
	v_lshl_add_u64 v[4:5], v[4:5], 0, v[8:9]
	v_cvt_pk_bf16_f32 v6, v0, v1
	v_cvt_pk_bf16_f32 v7, v2, v3
	global_store_dwordx2 v[4:5], v[6:7], off
	v_add_u32_e32 v4, s14, v10
	v_ashrrev_i32_e32 v4, 2, v4
	v_mul_lo_u32 v4, v4, 30
	v_bfe_u32 v5, v44, 3, 2
	v_add3_u32 v4, v5, v4, 26
	v_ashrrev_i32_e32 v5, 31, v4
	v_lshlrev_b64 v[4:5], 11, v[4:5]
	v_lshl_add_u64 v[4:5], s[8:9], 0, v[4:5]
	v_lshl_add_u64 v[4:5], v[40:41], 2, v[4:5]
	global_store_dwordx4 v[4:5], v[0:3], off nt

; #define HG_MFMA(a, b, c) __builtin_amdgcn_mfma_f32_32x32x16_bf16((a), (b), (c), 0, 0, 0)
;     __device__ __forceinline__ void small_pre(int row, int c0, int c1, SPre& sp) const { sp.ss = sumsq2[row]; sp.h0 = unpack4(*(const u32x2*)(HB + (size_t)row * DM + c0)); sp.h1 = unpack4(*(const u32x2*)(HB + (size_t)row * DM + c1)); }
; template <int K, class Epi>
; __device__ __forceinline__ void small_gemm(unsigned char* lds, const bf16_t* A, const bf16_t* Bt, int row0, int br0, int br1, const Epi& E) {
;     int tid = threadIdx.x; asm volatile("" : "+v"(tid));
;     const int w = __builtin_amdgcn_readfirstlane(tid >> 6), lane = tid & 63, r = lane & 31, hh = lane >> 5;
;     constexpr int ks = K >> 3, NS = ks >> 4, UNR = NS <= 8 ? NS : 11; const int k0 = w * ks + 8 * hh;
;     const bf16_t* ap = A + (size_t)(row0 + r) * K + k0; const bf16_t* b0p = Bt + (size_t)(br0 + r) * K + k0; const bf16_t* b1p = Bt + (size_t)(br1 + r) * K + k0;
;     typename Epi::SPre spre; const int srow = row0 + ((tid >> 3) & 31), sc4 = (tid & 7) * 4;
;     if (tid < 256) E.small_pre(srow, br0 + sc4, br1 + sc4, spre);
;     f32x16 acc0, acc1;
; #pragma unroll
;     for (int i = 0; i < 16; ++i) { acc0[i] = 0.f; acc1[i] = 0.f; }
; #pragma unroll UNR
;     for (int s = 0; s < NS; ++s) { const bf16x8 a = *(const bf16x8*)(ap + 16 * s), b0 = *(const bf16x8*)(b0p + 16 * s), b1 = *(const bf16x8*)(b1p + 16 * s);
;         acc0 = HG_MFMA(a, b0, acc0); acc1 = HG_MFMA(a, b1, acc1); }
;     float* part = (float*)lds + (size_t)w * (2 * 32 * SG_P);
.LBB0_630:
	s_or_b64 exec, exec, s[14:15]
	v_and_b32_e32 v76, 31, v45
	v_bfe_u32 v77, v45, 5, 1
	s_ashr_i32 s8, s21, 6
	s_waitcnt lgkmcnt(0)
	s_lshl_b32 s53, s8, 8
	s_lshl_b32 s52, s20, 11
	s_add_i32 s52, s52, s53
	s_add_u32 s54, s82, s52
	s_addc_u32 s55, s83, 0
	s_lshl_b32 s52, s19, 11
	s_add_i32 s52, s52, s53
	s_add_u32 s56, s12, s52
	s_addc_u32 s57, s13, 0
	s_add_u32 s58, s56, 0x10000
	s_addc_u32 s59, s57, 0
	v_and_b32_e32 v60, 63, v45
	v_lshrrev_b32_e32 v61, 4, v60
	v_and_b32_e32 v62, 7, v60
	v_xor_b32_e32 v62, v62, v61
	v_lshrrev_b32_e32 v61, 3, v60
	v_lshlrev_b32_e32 v62, 4, v62
	v_lshl_or_b32 v64, v61, 11, v62
	v_xor_b32_e32 v65, 64, v64
	v_add_u32_e32 v65, 0x4000, v65
	v_add_u32_e32 v66, 0x8000, v64
	v_xor_b32_e32 v67, 64, v64
	v_add_u32_e32 v67, 0xc000, v67
	global_load_dwordx4 v[88:91], v64, s[54:55]
	global_load_dwordx4 v[92:95], v65, s[54:55]
	global_load_dwordx4 v[96:99], v66, s[54:55]
	global_load_dwordx4 v[100:103], v67, s[54:55]
	global_load_dwordx4 v[104:107], v64, s[56:57]
	global_load_dwordx4 v[108:111], v65, s[56:57]
	global_load_dwordx4 v[112:115], v66, s[56:57]
	global_load_dwordx4 v[116:119], v67, s[56:57]
	global_load_dwordx4 v[120:123], v64, s[58:59]
	global_load_dwordx4 v[124:127], v65, s[58:59]
	global_load_dwordx4 v[128:131], v66, s[58:59]
	global_load_dwordx4 v[132:135], v67, s[58:59]
	global_load_dwordx4 v[136:139], v64, s[54:55] offset:128
	global_load_dwordx4 v[140:143], v65, s[54:55] offset:128
	global_load_dwordx4 v[144:147], v66, s[54:55] offset:128
	global_load_dwordx4 v[148:151], v67, s[54:55] offset:128
	global_load_dwordx4 v[152:155], v64, s[56:57] offset:128
	global_load_dwordx4 v[156:159], v65, s[56:57] offset:128
	global_load_dwordx4 v[160:163], v66, s[56:57] offset:128
	global_load_dwordx4 v[164:167], v67, s[56:57] offset:128
	global_load_dwordx4 v[168:171], v64, s[58:59] offset:128
	global_load_dwordx4 v[172:175], v65, s[58:59] offset:128
	global_load_dwordx4 v[180:183], v66, s[58:59] offset:128
	global_load_dwordx4 v[184:187], v67, s[58:59] offset:128
	s_mul_i32 s60, s8, 0x3000
	v_lshl_add_u32 v68, v60, 4, s60
	v_lshl_add_u32 v69, v76, 7, s60
	v_bfe_u32 v63, v76, 1, 3
	v_or_b32_e32 v46, 0, v77
	v_xor_b32_e32 v46, v46, v63
	v_lshl_add_u32 v46, v46, 4, v69
	v_or_b32_e32 v47, 2, v77
	v_xor_b32_e32 v47, v47, v63
	v_lshl_add_u32 v47, v47, 4, v69
	v_or_b32_e32 v48, 4, v77
	v_xor_b32_e32 v48, v48, v63
	v_lshl_add_u32 v48, v48, 4, v69
	v_or_b32_e32 v49, 6, v77
	v_xor_b32_e32 v49, v49, v63
	v_lshl_add_u32 v49, v49, 4, v69
	s_mulk_i32 s8, 0x2400
	v_lshlrev_b32_e32 v40, 2, v76
	s_add_i32 s8, s8, 0
	v_mul_u32_u24_e32 v58, 0x90, v77
	v_lshlrev_b32_e32 v54, 2, v58
	v_add3_u32 v55, s8, v40, v54
	v_add3_u32 v40, s8, v54, v40
	v_add_u32_e32 v54, 0x1000, v40
	v_add_u32_e32 v56, 0x400, v55
	v_add_u32_e32 v57, 0x1400, v40
	v_add_u32_e32 v58, 0xc00, v55
	v_add_u32_e32 v59, 0x1e00, v40
	s_waitcnt vmcnt(12)
	ds_write_b128 v68, v[88:91]
	ds_write_b128 v68, v[92:95] offset:1024
	ds_write_b128 v68, v[96:99] offset:2048
	ds_write_b128 v68, v[100:103] offset:3072
	ds_write_b128 v68, v[104:107] offset:4096
	ds_write_b128 v68, v[108:111] offset:5120
	ds_write_b128 v68, v[112:115] offset:6144
	ds_write_b128 v68, v[116:119] offset:7168
	ds_write_b128 v68, v[120:123] offset:8192
	ds_write_b128 v68, v[124:127] offset:9216
	ds_write_b128 v68, v[128:131] offset:10240
	ds_write_b128 v68, v[132:135] offset:11264
	s_waitcnt lgkmcnt(0)
	ds_read_b128 v[192:195], v46
	ds_read_b128 v[212:215], v46 offset:4096
	ds_read_b128 v[228:231], v46 offset:8192
	ds_read_b128 v[196:199], v47
	ds_read_b128 v[216:219], v47 offset:4096
	ds_read_b128 v[232:235], v47 offset:8192
	ds_read_b128 v[200:203], v48
	ds_read_b128 v[220:223], v48 offset:4096
	ds_read_b128 v[236:239], v48 offset:8192
	ds_read_b128 v[208:211], v49
	ds_read_b128 v[224:227], v49 offset:4096
	ds_read_b128 v[240:243], v49 offset:8192
	s_waitcnt lgkmcnt(9)
	v_mfma_f32_32x32x16_bf16 v[0:15], v[192:195], v[212:215], 0
	v_mfma_f32_32x32x16_bf16 v[16:31], v[192:195], v[228:231], 0
	s_waitcnt lgkmcnt(6)
	v_mfma_f32_32x32x16_bf16 v[0:15], v[196:199], v[216:219], v[0:15]
	v_mfma_f32_32x32x16_bf16 v[16:31], v[196:199], v[232:235], v[16:31]
	s_waitcnt lgkmcnt(3)
	v_mfma_f32_32x32x16_bf16 v[0:15], v[200:203], v[220:223], v[0:15]
	v_mfma_f32_32x32x16_bf16 v[16:31], v[200:203], v[236:239], v[16:31]
	s_waitcnt lgkmcnt(0)
	v_mfma_f32_32x32x16_bf16 v[0:15], v[208:211], v[224:227], v[0:15]
	v_mfma_f32_32x32x16_bf16 v[16:31], v[208:211], v[240:243], v[16:31]
	s_waitcnt vmcnt(0)
	ds_write_b128 v68, v[136:139]
	ds_write_b128 v68, v[140:143] offset:1024
	ds_write_b128 v68, v[144:147] offset:2048
	ds_write_b128 v68, v[148:151] offset:3072
	ds_write_b128 v68, v[152:155] offset:4096
	ds_write_b128 v68, v[156:159] offset:5120
	ds_write_b128 v68, v[160:163] offset:6144
	ds_write_b128 v68, v[164:167] offset:7168
	ds_write_b128 v68, v[168:171] offset:8192
	ds_write_b128 v68, v[172:175] offset:9216
	ds_write_b128 v68, v[180:183] offset:10240
	ds_write_b128 v68, v[184:187] offset:11264
	s_waitcnt lgkmcnt(0)
	ds_read_b128 v[192:195], v46
	ds_read_b128 v[212:215], v46 offset:4096
	ds_read_b128 v[228:231], v46 offset:8192
	ds_read_b128 v[196:199], v47
	ds_read_b128 v[216:219], v47 offset:4096
	ds_read_b128 v[232:235], v47 offset:8192
	ds_read_b128 v[200:203], v48
	ds_read_b128 v[220:223], v48 offset:4096
	ds_read_b128 v[236:239], v48 offset:8192
	ds_read_b128 v[208:211], v49
	ds_read_b128 v[224:227], v49 offset:4096
	ds_read_b128 v[240:243], v49 offset:8192
	s_waitcnt lgkmcnt(9)
	v_mfma_f32_32x32x16_bf16 v[0:15], v[192:195], v[212:215], v[0:15]
	v_mfma_f32_32x32x16_bf16 v[16:31], v[192:195], v[228:231], v[16:31]
	s_waitcnt lgkmcnt(6)
	v_mfma_f32_32x32x16_bf16 v[0:15], v[196:199], v[216:219], v[0:15]
	v_mfma_f32_32x32x16_bf16 v[16:31], v[196:199], v[232:235], v[16:31]
	s_waitcnt lgkmcnt(3)
	v_mfma_f32_32x32x16_bf16 v[0:15], v[200:203], v[220:223], v[0:15]
	v_mfma_f32_32x32x16_bf16 v[16:31], v[200:203], v[236:239], v[16:31]
	s_waitcnt lgkmcnt(0)
	v_mfma_f32_32x32x16_bf16 v[0:15], v[208:211], v[224:227], v[0:15]
	v_add_u32_e32 v50, 0x1600, v40
	v_add_u32_e32 v51, 0x800, v55
	v_add_u32_e32 v52, 0x1800, v40
	v_add_u32_e32 v53, 0x1c00, v40
	v_add_u32_e32 v40, 0x2000, v40
	v_mfma_f32_32x32x16_bf16 v[16:31], v[208:211], v[240:243], v[16:31]
	s_barrier
; __device__ __forceinline__ unsigned cvt_pk_bf16(float lo, float hi) { unsigned r; asm volatile("v_cvt_pk_bf16_f32 %0, %1, %2" : "=v"(r) : "v"(lo), "v"(hi)); return r; }
; template <int CTRL> __device__ __forceinline__ float dpp_step(float t) { return t + __builtin_bit_cast(float, __builtin_amdgcn_update_dpp(0, __builtin_bit_cast(int, t), CTRL, 0xF, 0xF, true)); }
; #define LDS_BARRIER() do { asm volatile("s_waitcnt lgkmcnt(0)" ::: "memory"); __builtin_amdgcn_s_barrier(); asm volatile("" ::: "memory"); } while (0)
; template <int K, class Epi>
; __device__ __forceinline__ void small_gemm(unsigned char* lds, const bf16_t* A, const bf16_t* Bt, int row0, int br0, int br1, const Epi& E) {
;     ...
;     float* part = (float*)lds + (size_t)w * (2 * 32 * SG_P);
; #pragma unroll
;     for (int g = 0; g < 4; ++g)
; #pragma unroll
;         for (int i = 0; i < 4; ++i) { part[(8 * g + 4 * hh + i) * SG_P + r] = acc0[4 * g + i]; part[(32 + 8 * g + 4 * hh + i) * SG_P + r] = acc1[4 * g + i]; }
;     LDS_BARRIER();
;     if (tid < 256) { const int row = tid >> 3, c4 = (tid & 7) * 4; f32x4 v0 = {0.f, 0.f, 0.f, 0.f}, v1 = {0.f, 0.f, 0.f, 0.f};
; #pragma unroll
;         for (int ww = 0; ww < 8; ++ww) { const float* pp = (const float*)lds + (size_t)ww * (2 * 32 * SG_P); v0 += *(const f32x4*)(pp + row * SG_P + c4); v1 += *(const f32x4*)(pp + (32 + row) * SG_P + c4); }
;         E.small(row0 + row, br0 + c4, br1 + c4, v0, v1, spre); }
;     __device__ __forceinline__ void small(int row, int c0, int c1, const f32x4& v0, const f32x4& v1, const SPre& sp) const {
;         float ss = 0.f;
; #pragma unroll
;         for (int gsel = 0; gsel < 2; ++gsel) { const int c = gsel ? c1 : c0; bf16_t* hb = HB + (size_t)row * DM + c; f32x4 h;
;             h = gsel ? sp.b1 : sp.b0;
;             h += (gsel ? v1 : v0);
;             u32x2 w; w.x = cvt_pk_bf16(h[0], h[1]); w.y = cvt_pk_bf16(h[2], h[3]); *(u32x2*)(HBo + (size_t)row * DM + c) = w;
;             ss += (h[0] * h[0] + h[1] * h[1]) + (h[2] * h[2] + h[3] * h[3]); }
;         ss = dpp_step<0x141>(dpp_step<0x4E>(dpp_step<0xB1>(ss)));
;         if ((threadIdx.x & 7) == 0) atomicAdd(sumsq + row, ss);
;     }
	s_nop 4
	ds_write2_b32 v55, v0, v1 offset1:36
	s_nop 5
	ds_write2_b32 v54, v16, v17 offset0:128 offset1:164
	ds_write2_b32 v55, v2, v3 offset0:72 offset1:108
	ds_write2_b32 v54, v18, v19 offset0:200 offset1:236
	ds_write2_b32 v56, v4, v5 offset0:32 offset1:68
	ds_write2_b32 v57, v20, v21 offset0:160 offset1:196
	ds_write2_b32 v56, v6, v7 offset0:104 offset1:140
	ds_write2_b32 v50, v22, v23 offset0:104 offset1:140
	ds_write2_b32 v51, v8, v9 offset0:64 offset1:100
	ds_write2_b32 v52, v24, v25 offset0:192 offset1:228
	ds_write2_b32 v51, v10, v11 offset0:136 offset1:172
	ds_write2_b32 v53, v26, v27 offset0:8 offset1:44
	ds_write2_b32 v58, v12, v13 offset0:96 offset1:132
	ds_write2_b32 v59, v28, v29 offset0:96 offset1:132
	ds_write2_b32 v58, v14, v15 offset0:168 offset1:204
	ds_write2_b32 v40, v30, v31 offset0:40 offset1:76
	s_waitcnt lgkmcnt(0)
	s_barrier
	s_and_saveexec_b64 s[8:9], s[6:7]
	s_cbranch_execz .LBB0_627
	v_ashrrev_i32_e32 v30, 3, v45
	v_mul_lo_u32 v0, v30, s17
	v_lshlrev_b32_e32 v1, 2, v43
	v_add3_u32 v31, 0, v0, v1
	ds_read_b128 v[0:3], v31
	ds_read_b128 v[4:7], v31 offset:4608
	ds_read_b128 v[8:11], v31 offset:9216
	ds_read_b128 v[12:15], v31 offset:64512
	v_lshlrev_b32_e32 v40, 1, v44
	s_waitcnt lgkmcnt(3)
	v_pk_add_f32 v[16:17], v[2:3], 0 op_sel_hi:[1,0]
	v_pk_add_f32 v[18:19], v[0:1], 0 op_sel_hi:[1,0]
	ds_read_b128 v[0:3], v31 offset:13824
	s_waitcnt lgkmcnt(3)
	v_pk_add_f32 v[20:21], v[6:7], 0 op_sel_hi:[1,0]
	v_pk_add_f32 v[22:23], v[4:5], 0 op_sel_hi:[1,0]
	ds_read_b128 v[4:7], v31 offset:18432
	s_waitcnt lgkmcnt(3)
	v_pk_add_f32 v[16:17], v[16:17], v[10:11]
	v_pk_add_f32 v[18:19], v[18:19], v[8:9]
	s_waitcnt lgkmcnt(1)
	v_pk_add_f32 v[20:21], v[20:21], v[2:3]
	ds_read_b128 v[8:11], v31 offset:23040
	v_pk_add_f32 v[22:23], v[22:23], v[0:1]
	ds_read_b128 v[0:3], v31 offset:27648
	s_waitcnt lgkmcnt(2)
	v_pk_add_f32 v[6:7], v[16:17], v[6:7]
	v_pk_add_f32 v[16:17], v[18:19], v[4:5]
	s_waitcnt lgkmcnt(1)
	v_pk_add_f32 v[10:11], v[20:21], v[10:11]
	v_pk_add_f32 v[24:25], v[22:23], v[8:9]
	s_waitcnt lgkmcnt(0)
	v_pk_add_f32 v[26:27], v[6:7], v[2:3]
	ds_read_b128 v[2:5], v31 offset:32256
	v_pk_add_f32 v[28:29], v[16:17], v[0:1]
	ds_read_b128 v[6:9], v31 offset:36864
	v_add_u32_e32 v0, 0xfc00, v31
	ds_read_b128 v[20:23], v31 offset:41472
	ds_read_b128 v[16:19], v0 offset:4608
	s_waitcnt lgkmcnt(3)
	v_pk_add_f32 v[4:5], v[10:11], v[4:5]
	v_pk_add_f32 v[10:11], v[24:25], v[2:3]
	ds_read_b128 v[0:3], v31 offset:46080
	s_waitcnt lgkmcnt(3)
	v_pk_add_f32 v[8:9], v[26:27], v[8:9]
	v_pk_add_f32 v[24:25], v[28:29], v[6:7]
	s_waitcnt lgkmcnt(2)
	v_pk_add_f32 v[22:23], v[4:5], v[22:23]
	ds_read_b128 v[4:7], v31 offset:50688
	v_pk_add_f32 v[20:21], v[10:11], v[20:21]
	s_waitcnt lgkmcnt(1)
	v_pk_add_f32 v[26:27], v[8:9], v[2:3]
	ds_read_b128 v[8:11], v31 offset:55296
	v_pk_add_f32 v[24:25], v[24:25], v[0:1]
	ds_read_b128 v[0:3], v31 offset:59904
	s_waitcnt lgkmcnt(2)
	v_pk_add_f32 v[4:5], v[20:21], v[4:5]
	v_pk_add_f32 v[6:7], v[22:23], v[6:7]
	s_waitcnt lgkmcnt(1)
	v_pk_add_f32 v[8:9], v[24:25], v[8:9]
	v_pk_add_f32 v[10:11], v[26:27], v[10:11]
	s_waitcnt lgkmcnt(0)
	v_pk_add_f32 v[0:1], v[4:5], v[0:1]
	v_pk_add_f32 v[2:3], v[6:7], v[2:3]
	v_pk_add_f32 v[6:7], v[8:9], v[12:13]
	v_pk_add_f32 v[8:9], v[0:1], v[16:17]
	v_add_u32_e32 v0, s20, v30
	v_pk_add_f32 v[4:5], v[10:11], v[14:15]
	v_ashrrev_i32_e32 v1, 31, v0
	v_lshlrev_b64 v[10:11], 11, v[0:1]
	v_pk_add_f32 v[4:5], v[38:39], v[4:5]
	v_pk_add_f32 v[6:7], v[36:37], v[6:7]
	v_lshl_add_u64 v[10:11], s[84:85], 0, v[10:11]
	v_cvt_pk_bf16_f32 v12, v6, v7
	v_cvt_pk_bf16_f32 v13, v4, v5
	v_mul_f32_e32 v7, v7, v7
	v_mul_f32_e32 v5, v5, v5
	v_pk_add_f32 v[2:3], v[2:3], v[18:19]
	v_lshl_add_u64 v[14:15], v[10:11], 0, v[40:41]
	v_fmac_f32_e32 v7, v6, v6
	v_fmac_f32_e32 v5, v4, v4
	global_store_dwordx2 v[14:15], v[12:13], off
	v_add_f32_e32 v12, v7, v5
	v_pk_add_f32 v[2:3], v[34:35], v[2:3]
	v_pk_add_f32 v[4:5], v[32:33], v[8:9]
	v_add_lshl_u32 v40, v43, s19, 1
	v_cvt_pk_bf16_f32 v6, v4, v5
	v_cvt_pk_bf16_f32 v7, v2, v3
	v_mul_f32_e32 v5, v5, v5
	v_mul_f32_e32 v3, v3, v3
	v_fmac_f32_e32 v5, v4, v4
	v_fmac_f32_e32 v3, v2, v2
	v_add_f32_e32 v2, v5, v3
	v_add_f32_e32 v2, v12, v2
	v_lshl_add_u64 v[8:9], v[10:11], 0, v[40:41]
	global_store_dwordx2 v[8:9], v[6:7], off offset:64
	v_add_f32_dpp v2, v2, v2 quad_perm:[1,0,3,2] row_mask:0xf bank_mask:0xf bound_ctrl:1
	s_nop 1
	v_add_f32_dpp v2, v2, v2 quad_perm:[2,3,0,1] row_mask:0xf bank_mask:0xf bound_ctrl:1
	s_nop 1
	v_mov_b32_dpp v3, v2 row_half_mirror row_mask:0xf bank_mask:0xf bound_ctrl:1
	s_and_b64 exec, exec, vcc
	s_cbranch_execz .LBB0_627
	v_lshl_add_u64 v[0:1], v[0:1], 2, s[10:11]
	v_add_f32_e32 v2, v2, v3
	global_atomic_add_f32 v[0:1], v2, off
	s_branch .LBB0_627

; #define HG_MFMA(a, b, c) __builtin_amdgcn_mfma_f32_32x32x16_bf16((a), (b), (c), 0, 0, 0)
;     __device__ __forceinline__ void small_pre(int row, int c0, int c1, SPre& sp) const { sp.ss = sumsq2[row]; sp.h0 = unpack4(*(const u32x2*)(HB + (size_t)row * DM + c0)); sp.h1 = unpack4(*(const u32x2*)(HB + (size_t)row * DM + c1)); }
; template <int K, class Epi>
; __device__ __forceinline__ void small_gemm(unsigned char* lds, const bf16_t* A, const bf16_t* Bt, int row0, int br0, int br1, const Epi& E) {
;     int tid = threadIdx.x; asm volatile("" : "+v"(tid));
;     const int w = __builtin_amdgcn_readfirstlane(tid >> 6), lane = tid & 63, r = lane & 31, hh = lane >> 5;
;     constexpr int ks = K >> 3, NS = ks >> 4, UNR = NS <= 8 ? NS : 11; const int k0 = w * ks + 8 * hh;
;     const bf16_t* ap = A + (size_t)(row0 + r) * K + k0; const bf16_t* b0p = Bt + (size_t)(br0 + r) * K + k0; const bf16_t* b1p = Bt + (size_t)(br1 + r) * K + k0;
;     typename Epi::SPre spre; const int srow = row0 + ((tid >> 3) & 31), sc4 = (tid & 7) * 4;
;     if (tid < 256) E.small_pre(srow, br0 + sc4, br1 + sc4, spre);
;     f32x16 acc0, acc1;
; #pragma unroll
;     for (int i = 0; i < 16; ++i) { acc0[i] = 0.f; acc1[i] = 0.f; }
; #pragma unroll UNR
;     for (int s = 0; s < NS; ++s) { const bf16x8 a = *(const bf16x8*)(ap + 16 * s), b0 = *(const bf16x8*)(b0p + 16 * s), b1 = *(const bf16x8*)(b1p + 16 * s);
;         acc0 = HG_MFMA(a, b0, acc0); acc1 = HG_MFMA(a, b1, acc1); }
;     float* part = (float*)lds + (size_t)w * (2 * 32 * SG_P);
.LBB0_898:
	s_or_b64 exec, exec, s[6:7]
	v_and_b32_e32 v76, 31, v45
	v_bfe_u32 v77, v45, 5, 1
	s_ashr_i32 s6, s21, 6
	s_or_b32 s21, s19, 32
	s_waitcnt lgkmcnt(0)
	s_lshl_b32 s53, s6, 8
	s_lshl_b32 s52, s20, 11
	s_add_i32 s52, s52, s53
	s_add_u32 s54, s84, s52
	s_addc_u32 s55, s85, 0
	s_lshl_b32 s52, s19, 11
	s_add_i32 s52, s52, s53
	s_add_u32 s56, s8, s52
	s_addc_u32 s57, s9, 0
	s_add_u32 s58, s56, 0x10000
	s_addc_u32 s59, s57, 0
	v_and_b32_e32 v60, 63, v45
	v_lshrrev_b32_e32 v61, 4, v60
	v_and_b32_e32 v62, 7, v60
	v_xor_b32_e32 v62, v62, v61
	v_lshrrev_b32_e32 v61, 3, v60
	v_lshlrev_b32_e32 v62, 4, v62
	v_lshl_or_b32 v64, v61, 11, v62
	v_xor_b32_e32 v65, 64, v64
	v_add_u32_e32 v65, 0x4000, v65
	v_add_u32_e32 v66, 0x8000, v64
	v_xor_b32_e32 v67, 64, v64
	v_add_u32_e32 v67, 0xc000, v67
	global_load_dwordx4 v[88:91], v64, s[54:55]
	global_load_dwordx4 v[92:95], v65, s[54:55]
	global_load_dwordx4 v[96:99], v66, s[54:55]
	global_load_dwordx4 v[100:103], v67, s[54:55]
	global_load_dwordx4 v[104:107], v64, s[56:57]
	global_load_dwordx4 v[108:111], v65, s[56:57]
	global_load_dwordx4 v[112:115], v66, s[56:57]
	global_load_dwordx4 v[116:119], v67, s[56:57]
	global_load_dwordx4 v[120:123], v64, s[58:59]
	global_load_dwordx4 v[124:127], v65, s[58:59]
	global_load_dwordx4 v[128:131], v66, s[58:59]
	global_load_dwordx4 v[132:135], v67, s[58:59]
	global_load_dwordx4 v[136:139], v64, s[54:55] offset:128
	global_load_dwordx4 v[140:143], v65, s[54:55] offset:128
	global_load_dwordx4 v[144:147], v66, s[54:55] offset:128
	global_load_dwordx4 v[148:151], v67, s[54:55] offset:128
	global_load_dwordx4 v[152:155], v64, s[56:57] offset:128
	global_load_dwordx4 v[156:159], v65, s[56:57] offset:128
	global_load_dwordx4 v[160:163], v66, s[56:57] offset:128
	global_load_dwordx4 v[164:167], v67, s[56:57] offset:128
	global_load_dwordx4 v[168:171], v64, s[58:59] offset:128
	global_load_dwordx4 v[172:175], v65, s[58:59] offset:128
	global_load_dwordx4 v[180:183], v66, s[58:59] offset:128
	global_load_dwordx4 v[184:187], v67, s[58:59] offset:128
	s_mul_i32 s60, s6, 0x3000
	v_lshl_add_u32 v68, v60, 4, s60
	v_lshl_add_u32 v69, v76, 7, s60
	v_bfe_u32 v63, v76, 1, 3
	v_or_b32_e32 v46, 0, v77
	v_xor_b32_e32 v46, v46, v63
	v_lshl_add_u32 v46, v46, 4, v69
	v_or_b32_e32 v47, 2, v77
	v_xor_b32_e32 v47, v47, v63
	v_lshl_add_u32 v47, v47, 4, v69
	v_or_b32_e32 v48, 4, v77
	v_xor_b32_e32 v48, v48, v63
	v_lshl_add_u32 v48, v48, 4, v69
	v_or_b32_e32 v49, 6, v77
	v_xor_b32_e32 v49, v49, v63
	v_lshl_add_u32 v49, v49, 4, v69
	s_mulk_i32 s6, 0x2400
	v_lshlrev_b32_e32 v32, 2, v76
	s_add_i32 s6, s6, 0
	v_mul_u32_u24_e32 v58, 0x90, v77
	v_lshlrev_b32_e32 v54, 2, v58
	v_add3_u32 v55, s6, v32, v54
	v_add3_u32 v32, s6, v54, v32
	v_add_u32_e32 v54, 0x1000, v32
	v_add_u32_e32 v56, 0x400, v55
	v_add_u32_e32 v57, 0x1400, v32
	v_add_u32_e32 v58, 0xc00, v55
	v_add_u32_e32 v59, 0x1e00, v32
	s_waitcnt vmcnt(12)
	ds_write_b128 v68, v[88:91]
	ds_write_b128 v68, v[92:95] offset:1024
	ds_write_b128 v68, v[96:99] offset:2048
	ds_write_b128 v68, v[100:103] offset:3072
	ds_write_b128 v68, v[104:107] offset:4096
	ds_write_b128 v68, v[108:111] offset:5120
	ds_write_b128 v68, v[112:115] offset:6144
	ds_write_b128 v68, v[116:119] offset:7168
	ds_write_b128 v68, v[120:123] offset:8192
	ds_write_b128 v68, v[124:127] offset:9216
	ds_write_b128 v68, v[128:131] offset:10240
	ds_write_b128 v68, v[132:135] offset:11264
	s_waitcnt lgkmcnt(0)
	ds_read_b128 v[192:195], v46
	ds_read_b128 v[212:215], v46 offset:4096
	ds_read_b128 v[228:231], v46 offset:8192
	ds_read_b128 v[196:199], v47
	ds_read_b128 v[216:219], v47 offset:4096
	ds_read_b128 v[232:235], v47 offset:8192
	ds_read_b128 v[200:203], v48
	ds_read_b128 v[220:223], v48 offset:4096
	ds_read_b128 v[236:239], v48 offset:8192
	ds_read_b128 v[208:211], v49
	ds_read_b128 v[224:227], v49 offset:4096
	ds_read_b128 v[240:243], v49 offset:8192
	s_waitcnt lgkmcnt(9)
	v_mfma_f32_32x32x16_bf16 v[0:15], v[192:195], v[212:215], 0
	v_mfma_f32_32x32x16_bf16 v[16:31], v[192:195], v[228:231], 0
	s_waitcnt lgkmcnt(6)
	v_mfma_f32_32x32x16_bf16 v[0:15], v[196:199], v[216:219], v[0:15]
	v_mfma_f32_32x32x16_bf16 v[16:31], v[196:199], v[232:235], v[16:31]
	s_waitcnt lgkmcnt(3)
	v_mfma_f32_32x32x16_bf16 v[0:15], v[200:203], v[220:223], v[0:15]
	v_mfma_f32_32x32x16_bf16 v[16:31], v[200:203], v[236:239], v[16:31]
	s_waitcnt lgkmcnt(0)
	v_mfma_f32_32x32x16_bf16 v[0:15], v[208:211], v[224:227], v[0:15]
	v_mfma_f32_32x32x16_bf16 v[16:31], v[208:211], v[240:243], v[16:31]
	s_waitcnt vmcnt(0)
	ds_write_b128 v68, v[136:139]
	ds_write_b128 v68, v[140:143] offset:1024
	ds_write_b128 v68, v[144:147] offset:2048
	ds_write_b128 v68, v[148:151] offset:3072
	ds_write_b128 v68, v[152:155] offset:4096
	ds_write_b128 v68, v[156:159] offset:5120
	ds_write_b128 v68, v[160:163] offset:6144
	ds_write_b128 v68, v[164:167] offset:7168
	ds_write_b128 v68, v[168:171] offset:8192
	ds_write_b128 v68, v[172:175] offset:9216
	ds_write_b128 v68, v[180:183] offset:10240
	ds_write_b128 v68, v[184:187] offset:11264
	s_waitcnt lgkmcnt(0)
	ds_read_b128 v[192:195], v46
	ds_read_b128 v[212:215], v46 offset:4096
	ds_read_b128 v[228:231], v46 offset:8192
	ds_read_b128 v[196:199], v47
	ds_read_b128 v[216:219], v47 offset:4096
	ds_read_b128 v[232:235], v47 offset:8192
	ds_read_b128 v[200:203], v48
	ds_read_b128 v[220:223], v48 offset:4096
	ds_read_b128 v[236:239], v48 offset:8192
	ds_read_b128 v[208:211], v49
	ds_read_b128 v[224:227], v49 offset:4096
	ds_read_b128 v[240:243], v49 offset:8192
	s_waitcnt lgkmcnt(9)
	v_mfma_f32_32x32x16_bf16 v[0:15], v[192:195], v[212:215], v[0:15]
	v_mfma_f32_32x32x16_bf16 v[16:31], v[192:195], v[228:231], v[16:31]
	s_waitcnt lgkmcnt(6)
	v_mfma_f32_32x32x16_bf16 v[0:15], v[196:199], v[216:219], v[0:15]
	v_mfma_f32_32x32x16_bf16 v[16:31], v[196:199], v[232:235], v[16:31]
	s_waitcnt lgkmcnt(3)
	v_mfma_f32_32x32x16_bf16 v[0:15], v[200:203], v[220:223], v[0:15]
	v_mfma_f32_32x32x16_bf16 v[16:31], v[200:203], v[236:239], v[16:31]
	s_waitcnt lgkmcnt(0)
	v_mfma_f32_32x32x16_bf16 v[0:15], v[208:211], v[224:227], v[0:15]
	v_add_u32_e32 v50, 0x1600, v32
	v_add_u32_e32 v51, 0x800, v55
	v_add_u32_e32 v52, 0x1800, v32
	v_add_u32_e32 v53, 0x1c00, v32
	v_add_u32_e32 v32, 0x2000, v32
	v_mfma_f32_32x32x16_bf16 v[16:31], v[208:211], v[240:243], v[16:31]
	s_barrier
; __device__ __forceinline__ unsigned cvt_pk_bf16(float lo, float hi) { unsigned r; asm volatile("v_cvt_pk_bf16_f32 %0, %1, %2" : "=v"(r) : "v"(lo), "v"(hi)); return r; }
; __device__ __forceinline__ float sigmoidf_(float x) { return frcp(1.0f + __expf(-x)); }
; template <int K, class Epi>
; __device__ __forceinline__ void small_gemm(unsigned char* lds, const bf16_t* A, const bf16_t* Bt, int row0, int br0, int br1, const Epi& E) {
;     ...
;     float* part = (float*)lds + (size_t)w * (2 * 32 * SG_P);
; #pragma unroll
;     for (int g = 0; g < 4; ++g)
; #pragma unroll
;         for (int i = 0; i < 4; ++i) { part[(8 * g + 4 * hh + i) * SG_P + r] = acc0[4 * g + i]; part[(32 + 8 * g + 4 * hh + i) * SG_P + r] = acc1[4 * g + i]; }
;     LDS_BARRIER();
;     if (tid < 256) { const int row = tid >> 3, c4 = (tid & 7) * 4; f32x4 v0 = {0.f, 0.f, 0.f, 0.f}, v1 = {0.f, 0.f, 0.f, 0.f};
; #pragma unroll
;         for (int ww = 0; ww < 8; ++ww) { const float* pp = (const float*)lds + (size_t)ww * (2 * 32 * SG_P); v0 += *(const f32x4*)(pp + row * SG_P + c4); v1 += *(const f32x4*)(pp + (32 + row) * SG_P + c4); }
;         E.small(row0 + row, br0 + c4, br1 + c4, v0, v1, spre); }
;     __device__ __forceinline__ void small_pre(int row, int c0, int c1, SPre& sp) const { sp.ss = sumsq2[row]; sp.h0 = unpack4(*(const u32x2*)(HB + (size_t)row * DM + c0)); sp.h1 = unpack4(*(const u32x2*)(HB + (size_t)row * DM + c1)); }
;     __device__ __forceinline__ void small(int row, int c0, int c1, const f32x4& v0, const f32x4& v1, const SPre& sp) const {
;         const float rstd = rsqrtf(sp.ss * (1.0f / DM) + EPS); float ss = 0.f;
; #pragma unroll
;         for (int gsel = 0; gsel < 2; ++gsel) { const int c = gsel ? c1 : c0; const f32x4 x = gsel ? v1 : v0; const size_t o = (size_t)row * DM + c;
;             f32x4 h = gsel ? sp.h1 : sp.h0; const f32x4 pp = unpack4(*(const u32x2*)(PPb + o));
; #pragma unroll
;             for (int j = 0; j < 4; ++j) h[j] += sigmoidf_(x[j] * rstd) * pp[j];
;             u32x2 w; w.x = cvt_pk_bf16(h[0], h[1]); w.y = cvt_pk_bf16(h[2], h[3]); *(u32x2*)(H3 + o) = w;
;             ss += (h[0] * h[0] + h[1] * h[1]) + (h[2] * h[2] + h[3] * h[3]); }
;         ss = dpp_step<0x141>(dpp_step<0x4E>(dpp_step<0xB1>(ss)));
;         if ((threadIdx.x & 7) == 0) atomicAdd(sumsq3 + row, ss);
;     }
	s_nop 4
	ds_write2_b32 v55, v0, v1 offset1:36
	s_nop 5
	ds_write2_b32 v54, v16, v17 offset0:128 offset1:164
	ds_write2_b32 v55, v2, v3 offset0:72 offset1:108
	ds_write2_b32 v54, v18, v19 offset0:200 offset1:236
	ds_write2_b32 v56, v4, v5 offset0:32 offset1:68
	ds_write2_b32 v57, v20, v21 offset0:160 offset1:196
	ds_write2_b32 v56, v6, v7 offset0:104 offset1:140
	ds_write2_b32 v50, v22, v23 offset0:104 offset1:140
	ds_write2_b32 v51, v8, v9 offset0:64 offset1:100
	ds_write2_b32 v52, v24, v25 offset0:192 offset1:228
	ds_write2_b32 v51, v10, v11 offset0:136 offset1:172
	ds_write2_b32 v53, v26, v27 offset0:8 offset1:44
	ds_write2_b32 v58, v12, v13 offset0:96 offset1:132
	ds_write2_b32 v59, v28, v29 offset0:96 offset1:132
	ds_write2_b32 v58, v14, v15 offset0:168 offset1:204
	ds_write2_b32 v32, v30, v31 offset0:40 offset1:76
	s_waitcnt lgkmcnt(0)
	s_barrier
	s_and_saveexec_b64 s[6:7], s[4:5]
	s_cbranch_execz .LBB0_895
	v_ashrrev_i32_e32 v4, 3, v45
	v_add_u32_e32 v0, s20, v4
	v_ashrrev_i32_e32 v1, 31, v0
	v_lshlrev_b64 v[30:31], 10, v[0:1]
	v_or3_b32 v2, v43, s19, v30
	v_mov_b32_e32 v3, v31
	v_lshlrev_b64 v[80:81], 1, v[2:3]
	v_lshl_add_u64 v[2:3], s[82:83], 0, v[80:81]
	global_load_dwordx2 v[82:83], v[2:3], off
	v_lshlrev_b32_e32 v2, 2, v43
	v_mul_lo_u32 v4, v4, s16
	v_mul_f32_e32 v3, 0x4b800000, v44
	v_cmp_gt_f32_e64 s[4:5], s17, v44
	v_add3_u32 v32, 0, v4, v2
	v_add_u32_e32 v76, 0xfc00, v32
	v_cndmask_b32_e64 v3, v44, v3, s[4:5]
	v_rsq_f32_e32 v86, v3
	ds_read_b128 v[2:5], v32 offset:4608
	ds_read_b128 v[6:9], v32 offset:9216
	ds_read_b128 v[10:13], v32 offset:13824
	ds_read_b128 v[14:17], v32 offset:18432
	ds_read_b128 v[18:21], v32 offset:23040
	ds_read_b128 v[22:25], v32 offset:27648
	ds_read_b128 v[26:29], v32 offset:36864
	ds_read_b128 v[44:47], v32 offset:41472
	ds_read_b128 v[48:51], v32 offset:46080
	ds_read_b128 v[52:55], v32 offset:50688
	ds_read_b128 v[56:59], v32 offset:55296
	ds_read_b128 v[60:63], v32 offset:59904
	ds_read_b128 v[64:67], v32
	ds_read_b128 v[68:71], v32 offset:64512
	ds_read_b128 v[72:75], v32 offset:32256
	ds_read_b128 v[76:79], v76 offset:4608
	v_or3_b32 v30, v43, s21, v30
	s_waitcnt lgkmcnt(3)
	v_pk_add_f32 v[66:67], v[66:67], 0 op_sel_hi:[1,0]
	v_pk_add_f32 v[64:65], v[64:65], 0 op_sel_hi:[1,0]
	v_pk_add_f32 v[8:9], v[66:67], v[8:9]
	v_pk_add_f32 v[6:7], v[64:65], v[6:7]
	v_pk_add_f32 v[8:9], v[8:9], v[16:17]
	v_pk_add_f32 v[6:7], v[6:7], v[14:15]
	v_pk_add_f32 v[8:9], v[8:9], v[24:25]
	v_pk_add_f32 v[6:7], v[6:7], v[22:23]
	v_pk_add_f32 v[8:9], v[8:9], v[28:29]
	v_pk_add_f32 v[6:7], v[6:7], v[26:27]
	v_pk_add_f32 v[8:9], v[8:9], v[50:51]
	v_pk_add_f32 v[6:7], v[6:7], v[48:49]
	v_mul_f32_e32 v32, 0x45800000, v86
	v_pk_add_f32 v[8:9], v[8:9], v[58:59]
	v_pk_add_f32 v[6:7], v[6:7], v[56:57]
	v_cndmask_b32_e64 v32, v86, v32, s[4:5]
	s_waitcnt lgkmcnt(2)
	v_pk_add_f32 v[8:9], v[8:9], v[70:71]
	v_pk_add_f32 v[6:7], v[6:7], v[68:69]
	v_mul_f32_e32 v8, v32, v8
	v_mul_f32_e32 v6, v32, v6
	v_mul_f32_e32 v7, v32, v7
	v_mul_f32_e32 v9, v32, v9
	v_mul_f32_e32 v6, 0xbfb8aa3b, v6
	v_mul_f32_e32 v7, 0xbfb8aa3b, v7
	v_mul_f32_e32 v8, 0xbfb8aa3b, v8
	v_mul_f32_e32 v9, 0xbfb8aa3b, v9
	v_exp_f32_e32 v6, v6
	v_exp_f32_e32 v7, v7
	v_exp_f32_e32 v8, v8
	v_exp_f32_e32 v9, v9
	v_add_f32_e32 v6, 1.0, v6
	v_add_f32_e32 v7, 1.0, v7
	v_add_f32_e32 v8, 1.0, v8
	v_add_f32_e32 v9, 1.0, v9
	v_rcp_f32_e32 v6, v6
	v_rcp_f32_e32 v7, v7
	v_rcp_f32_e32 v8, v8
	v_rcp_f32_e32 v9, v9
	v_lshlrev_b64 v[30:31], 1, v[30:31]
	v_lshl_add_u64 v[80:81], s[68:69], 0, v[80:81]
	v_lshl_add_u64 v[84:85], s[82:83], 0, v[30:31]
	v_pk_add_f32 v[4:5], v[4:5], 0 op_sel_hi:[1,0]
	v_pk_add_f32 v[2:3], v[2:3], 0 op_sel_hi:[1,0]
	v_pk_add_f32 v[4:5], v[4:5], v[12:13]
	v_pk_add_f32 v[2:3], v[2:3], v[10:11]
	v_pk_add_f32 v[4:5], v[4:5], v[20:21]
	v_pk_add_f32 v[2:3], v[2:3], v[18:19]
	s_waitcnt lgkmcnt(1)
	v_pk_add_f32 v[4:5], v[4:5], v[74:75]
	v_pk_add_f32 v[2:3], v[2:3], v[72:73]
	v_pk_add_f32 v[4:5], v[4:5], v[46:47]
	v_pk_add_f32 v[2:3], v[2:3], v[44:45]
	v_pk_add_f32 v[4:5], v[4:5], v[54:55]
	v_pk_add_f32 v[2:3], v[2:3], v[52:53]
	v_pk_add_f32 v[4:5], v[4:5], v[62:63]
	v_pk_add_f32 v[2:3], v[2:3], v[60:61]
	s_waitcnt lgkmcnt(0)
	v_pk_add_f32 v[4:5], v[4:5], v[78:79]
	v_pk_add_f32 v[2:3], v[2:3], v[76:77]
	v_mul_f32_e32 v5, v32, v5
	v_mul_f32_e32 v3, v32, v3
	v_mul_f32_e32 v2, v32, v2
	v_mul_f32_e32 v4, v32, v4
	v_mul_f32_e32 v3, 0xbfb8aa3b, v3
	v_mul_f32_e32 v5, 0xbfb8aa3b, v5
	v_mul_f32_e32 v2, 0xbfb8aa3b, v2
	v_mul_f32_e32 v4, 0xbfb8aa3b, v4
	v_exp_f32_e32 v3, v3
	v_exp_f32_e32 v5, v5
	v_exp_f32_e32 v2, v2
	s_waitcnt vmcnt(0)
	v_lshlrev_b32_e32 v14, 16, v82
	v_and_b32_e32 v15, 0xffff0000, v82
	v_lshlrev_b32_e32 v16, 16, v83
	v_and_b32_e32 v17, 0xffff0000, v83
	v_fmac_f32_e32 v39, v6, v14
	v_fmac_f32_e32 v41, v7, v15
	v_fmac_f32_e32 v40, v8, v16
	v_fmac_f32_e32 v42, v9, v17
	v_cvt_pk_bf16_f32 v6, v39, v41
	v_cvt_pk_bf16_f32 v7, v40, v42
	global_store_dwordx2 v[80:81], v[6:7], off
	global_load_dwordx2 v[6:7], v[84:85], off
	v_exp_f32_e32 v4, v4
	v_add_f32_e32 v3, 1.0, v3
	v_add_f32_e32 v5, 1.0, v5
	v_add_f32_e32 v2, 1.0, v2
	v_add_f32_e32 v4, 1.0, v4
	v_rcp_f32_e32 v3, v3
	v_rcp_f32_e32 v5, v5
	v_rcp_f32_e32 v2, v2
	v_rcp_f32_e32 v4, v4
	v_mul_f32_e32 v10, v41, v41
	v_mul_f32_e32 v11, v42, v42
	v_fmac_f32_e32 v10, v39, v39
	v_fmac_f32_e32 v11, v40, v40
	v_add_f32_e32 v10, v10, v11
	v_lshl_add_u64 v[8:9], s[68:69], 0, v[30:31]
	s_waitcnt vmcnt(0)
	v_lshlrev_b32_e32 v11, 16, v6
	v_and_b32_e32 v6, 0xffff0000, v6
	v_lshlrev_b32_e32 v12, 16, v7
	v_and_b32_e32 v7, 0xffff0000, v7
	v_fmac_f32_e32 v37, v3, v6
	v_fmac_f32_e32 v38, v5, v7
	v_fmac_f32_e32 v35, v2, v11
	v_fmac_f32_e32 v36, v4, v12
	v_mul_f32_e32 v4, v37, v37
	v_mul_f32_e32 v5, v38, v38
	v_cvt_pk_bf16_f32 v2, v35, v37
	v_fmac_f32_e32 v4, v35, v35
	v_fmac_f32_e32 v5, v36, v36
	v_cvt_pk_bf16_f32 v3, v36, v38
	global_store_dwordx2 v[8:9], v[2:3], off
	v_add_f32_e32 v2, v4, v5
	v_add_f32_e32 v2, v10, v2
	s_nop 1
	v_add_f32_dpp v2, v2, v2 quad_perm:[1,0,3,2] row_mask:0xf bank_mask:0xf bound_ctrl:1
	s_nop 1
	v_add_f32_dpp v2, v2, v2 quad_perm:[2,3,0,1] row_mask:0xf bank_mask:0xf bound_ctrl:1
	s_nop 1
	v_mov_b32_dpp v3, v2 row_half_mirror row_mask:0xf bank_mask:0xf bound_ctrl:1
	s_and_b64 exec, exec, vcc
	s_cbranch_execz .LBB0_895
	v_lshl_add_u64 v[0:1], v[0:1], 2, s[10:11]
	v_add_f32_e32 v2, v2, v3
	global_atomic_add_f32 v[0:1], v2, off
	s_branch .LBB0_895
